# v21 + attention body: K/V fragment ds_reads issued at s_setprio 3 whatever quarter of the ladder the wave is in
# baseline (speedup 1.0000x reference)
.Lat1_dispatch:
	s_cbranch_scc1 .LBB0_539
	s_cbranch_vccnz .Lat1_skip
	s_and_b64 vcc, exec, s[22:23]
	s_cbranch_vccnz .Lat1_nodma
	s_setprio 3
	v_add_u32_e32 v14, s100, v0
	v_add_u32_e32 v15, s100, v212
	v_add_u32_e32 v176, s100, v213
	v_add_u32_e32 v177, s100, v219
	ds_read_b128 v[144:147], v14 offset:0
	ds_read_b128 v[148:151], v15 offset:0
	ds_read_b128 v[152:155], v176 offset:0
	ds_read_b128 v[156:159], v177 offset:0
	ds_read_b128 v[160:163], v14 offset:8192
	ds_read_b128 v[164:167], v15 offset:8192
	ds_read_b128 v[168:171], v176 offset:8192
	ds_read_b128 v[172:175], v177 offset:8192
	ds_read_b128 v[2:5], v14 offset:16384
	ds_read_b128 v[6:9], v15 offset:16384
	ds_read_b128 v[10:13], v176 offset:16384
	ds_read_b128 v[238:241], v177 offset:16384
	s_waitcnt lgkmcnt(8)
	v_mfma_f32_32x32x16_bf16 v[80:95], v[144:147], v[132:135], 0
	v_mfma_f32_32x32x16_bf16 v[80:95], v[148:151], v[128:131], v[80:95]
	v_mfma_f32_32x32x16_bf16 v[80:95], v[152:155], v[124:127], v[80:95]
	v_mfma_f32_32x32x16_bf16 v[80:95], v[156:159], v[120:123], v[80:95]
	ds_read_b128 v[144:147], v14 offset:4096
	ds_read_b128 v[148:151], v15 offset:4096
	ds_read_b128 v[152:155], v176 offset:4096
	ds_read_b128 v[156:159], v177 offset:4096
	s_waitcnt lgkmcnt(8)
	v_mfma_f32_32x32x16_bf16 v[80:95], v[160:163], v[116:119], v[80:95]
	v_mfma_f32_32x32x16_bf16 v[80:95], v[164:167], v[112:115], v[80:95]
	v_mfma_f32_32x32x16_bf16 v[80:95], v[168:171], v[108:111], v[80:95]
	v_mfma_f32_32x32x16_bf16 v[80:95], v[172:175], v[104:107], v[80:95]
	ds_read_b128 v[160:163], v14 offset:12288
	ds_read_b128 v[164:167], v15 offset:12288
	ds_read_b128 v[168:171], v176 offset:12288
	ds_read_b128 v[172:175], v177 offset:12288
	s_waitcnt lgkmcnt(8)
	v_mfma_f32_32x32x16_bf16 v[80:95], v[2:5], v[100:103], v[80:95]
	v_mfma_f32_32x32x16_bf16 v[80:95], v[6:9], v[140:143], v[80:95]
	v_mfma_f32_32x32x16_bf16 v[80:95], v[10:13], v[96:99], v[80:95]
	v_mfma_f32_32x32x16_bf16 v[80:95], v[238:241], v[136:139], v[80:95]
	s_setprio 2
	s_setprio 3
	ds_read_b128 v[2:5], v14 offset:20480
	ds_read_b128 v[6:9], v15 offset:20480
	ds_read_b128 v[10:13], v176 offset:20480
	ds_read_b128 v[238:241], v177 offset:20480
	s_setprio 2
	s_waitcnt lgkmcnt(8)
	v_mfma_f32_32x32x16_bf16 v[184:199], v[144:147], v[132:135], 0
	v_mfma_f32_32x32x16_bf16 v[184:199], v[148:151], v[128:131], v[184:199]
	v_mfma_f32_32x32x16_bf16 v[184:199], v[152:155], v[124:127], v[184:199]
	v_mfma_f32_32x32x16_bf16 v[184:199], v[156:159], v[120:123], v[184:199]
	s_setprio 3
	ds_read_b128 v[144:147], v14 offset:24576
	ds_read_b128 v[148:151], v14 offset:28672
	ds_read_b128 v[152:155], v14 offset:32768
	ds_read_b128 v[156:159], v14 offset:36864
	s_setprio 2
	s_waitcnt lgkmcnt(8)
	v_mfma_f32_32x32x16_bf16 v[184:199], v[160:163], v[116:119], v[184:199]
	v_med3_f32 v80, v80, s4, v236
	v_exp_f32_e32 v80, v80
	v_med3_f32 v81, v81, s4, v236
	v_exp_f32_e32 v81, v81
	v_mfma_f32_32x32x16_bf16 v[184:199], v[164:167], v[112:115], v[184:199]
	v_med3_f32 v82, v82, s4, v236
	v_exp_f32_e32 v82, v82
	v_med3_f32 v83, v83, s4, v236
	v_exp_f32_e32 v83, v83
	v_mfma_f32_32x32x16_bf16 v[184:199], v[168:171], v[108:111], v[184:199]
	v_med3_f32 v84, v84, s4, v236
	v_exp_f32_e32 v84, v84
	v_med3_f32 v85, v85, s4, v236
	v_exp_f32_e32 v85, v85
	v_mfma_f32_32x32x16_bf16 v[184:199], v[172:175], v[104:107], v[184:199]
	v_med3_f32 v86, v86, s4, v236
	v_exp_f32_e32 v86, v86
	v_med3_f32 v87, v87, s4, v236
	v_exp_f32_e32 v87, v87
	s_setprio 3
	ds_read_b128 v[160:163], v15 offset:24576
	ds_read_b128 v[164:167], v15 offset:28672
	ds_read_b128 v[168:171], v15 offset:32768
	ds_read_b128 v[172:175], v15 offset:36864
	s_setprio 2
	s_waitcnt lgkmcnt(8)
	v_mfma_f32_32x32x16_bf16 v[184:199], v[2:5], v[100:103], v[184:199]
	v_med3_f32 v88, v88, s4, v236
	v_exp_f32_e32 v88, v88
	v_med3_f32 v89, v89, s4, v236
	v_exp_f32_e32 v89, v89
	v_add_f32_e32 v200, v80, v81
	v_add_f32_e32 v200, v200, v82
	v_mfma_f32_32x32x16_bf16 v[184:199], v[6:9], v[140:143], v[184:199]
	v_med3_f32 v90, v90, s4, v236
	v_exp_f32_e32 v90, v90
	v_med3_f32 v91, v91, s4, v236
	v_exp_f32_e32 v91, v91
	v_add_f32_e32 v200, v200, v83
	v_add_f32_e32 v200, v200, v84
	v_mfma_f32_32x32x16_bf16 v[184:199], v[10:13], v[96:99], v[184:199]
	v_med3_f32 v92, v92, s4, v236
	v_exp_f32_e32 v92, v92
	v_med3_f32 v93, v93, s4, v236
	v_exp_f32_e32 v93, v93
	v_add_f32_e32 v200, v200, v85
	v_add_f32_e32 v200, v200, v86
	v_mfma_f32_32x32x16_bf16 v[184:199], v[238:241], v[136:139], v[184:199]
	v_med3_f32 v94, v94, s4, v236
	v_exp_f32_e32 v94, v94
	v_med3_f32 v95, v95, s4, v236
	v_exp_f32_e32 v95, v95
	v_add_f32_e32 v200, v200, v87
	s_setprio 1
	s_setprio 3
	ds_read_b128 v[2:5], v176 offset:24576
	ds_read_b128 v[6:9], v176 offset:28672
	ds_read_b128 v[10:13], v176 offset:32768
	ds_read_b128 v[238:241], v176 offset:36864
	s_setprio 1
	v_cvt_pk_bf16_f32 v80, v80, v81
	v_cvt_pk_bf16_f32 v81, v82, v83
	v_cvt_pk_bf16_f32 v82, v84, v85
	v_cvt_pk_bf16_f32 v83, v86, v87
	v_add_f32_e32 v200, v200, v88
	v_add_f32_e32 v200, v200, v89
	s_waitcnt lgkmcnt(8)
	v_mfma_f32_32x32x16_bf16 v[64:79], v[80:83], v[144:147], v[64:79]
	v_med3_f32 v184, v184, s4, v236
	v_exp_f32_e32 v184, v184
	v_med3_f32 v185, v185, s4, v236
	v_exp_f32_e32 v185, v185
	v_add_f32_e32 v200, v200, v90
	v_add_f32_e32 v200, v200, v91
	v_mfma_f32_32x32x16_bf16 v[48:63], v[80:83], v[148:151], v[48:63]
	v_med3_f32 v186, v186, s4, v236
	v_exp_f32_e32 v186, v186
	v_med3_f32 v187, v187, s4, v236
	v_exp_f32_e32 v187, v187
	v_add_f32_e32 v200, v200, v92
	v_add_f32_e32 v200, v200, v93
	v_mfma_f32_32x32x16_bf16 v[32:47], v[80:83], v[152:155], v[32:47]
	v_med3_f32 v188, v188, s4, v236
	v_exp_f32_e32 v188, v188
	v_med3_f32 v189, v189, s4, v236
	v_exp_f32_e32 v189, v189
	v_add_f32_e32 v200, v200, v94
	v_add_f32_e32 v200, v200, v95
	v_mfma_f32_32x32x16_bf16 v[16:31], v[80:83], v[156:159], v[16:31]
	v_med3_f32 v190, v190, s4, v236
	v_exp_f32_e32 v190, v190
	v_med3_f32 v191, v191, s4, v236
	v_exp_f32_e32 v191, v191
	v_cvt_pk_bf16_f32 v84, v88, v89
	v_cvt_pk_bf16_f32 v85, v90, v91
	v_cvt_pk_bf16_f32 v86, v92, v93
	v_cvt_pk_bf16_f32 v87, v94, v95
	s_setprio 3
	ds_read_b128 v[144:147], v177 offset:24576
	ds_read_b128 v[148:151], v177 offset:28672
	ds_read_b128 v[152:155], v177 offset:32768
	ds_read_b128 v[156:159], v177 offset:36864
	s_setprio 1
	s_waitcnt lgkmcnt(8)
	v_mfma_f32_32x32x16_bf16 v[64:79], v[84:87], v[160:163], v[64:79]
	v_med3_f32 v192, v192, s4, v236
	v_exp_f32_e32 v192, v192
	v_med3_f32 v193, v193, s4, v236
	v_exp_f32_e32 v193, v193
	v_add_f32_e32 v201, v184, v185
	v_add_f32_e32 v201, v201, v186
	v_mfma_f32_32x32x16_bf16 v[48:63], v[84:87], v[164:167], v[48:63]
	v_med3_f32 v194, v194, s4, v236
	v_exp_f32_e32 v194, v194
	v_med3_f32 v195, v195, s4, v236
	v_exp_f32_e32 v195, v195
	v_add_f32_e32 v201, v201, v187
	v_add_f32_e32 v201, v201, v188
	v_mfma_f32_32x32x16_bf16 v[32:47], v[84:87], v[168:171], v[32:47]
	v_med3_f32 v196, v196, s4, v236
	v_exp_f32_e32 v196, v196
	v_med3_f32 v197, v197, s4, v236
	v_exp_f32_e32 v197, v197
	v_add_f32_e32 v201, v201, v189
	v_mfma_f32_32x32x16_bf16 v[16:31], v[84:87], v[172:175], v[16:31]
	v_med3_f32 v198, v198, s4, v236
	v_exp_f32_e32 v198, v198
	v_med3_f32 v199, v199, s4, v236
	v_exp_f32_e32 v199, v199
	v_add_f32_e32 v201, v201, v190
	v_cvt_pk_bf16_f32 v184, v184, v185
	v_cvt_pk_bf16_f32 v185, v186, v187
	v_cvt_pk_bf16_f32 v186, v188, v189
	v_cvt_pk_bf16_f32 v187, v190, v191
	v_add_f32_e32 v201, v201, v191
	s_setprio 0
	s_waitcnt lgkmcnt(4)
	v_mfma_f32_32x32x16_bf16 v[64:79], v[184:187], v[2:5], v[64:79]
	v_mad_u64_u32 v[202:203], s[10:11], s86, v228, v[180:181]
	s_mul_i32 s10, s7, 0xa000
	s_add_i32 s10, s9, s10
	s_mov_b32 m0, s10
	v_lshl_add_u64 v[204:205], v[202:203], 0, s[94:95]
	global_load_lds_dwordx4 v[202:203], off
	v_add_f32_e32 v201, v201, v192
	v_add_f32_e32 v201, v201, v193
	v_add_f32_e32 v201, v201, v194
	v_mfma_f32_32x32x16_bf16 v[48:63], v[184:187], v[6:9], v[48:63]
	s_add_i32 m0, s10, 0x2000
	v_lshl_add_u64 v[202:203], v[202:203], 0, s[96:97]
	global_load_lds_dwordx4 v[204:205], off
	v_add_f32_e32 v201, v201, v195
	v_add_f32_e32 v201, v201, v196
	v_add_f32_e32 v201, v201, v197
	v_mfma_f32_32x32x16_bf16 v[32:47], v[184:187], v[10:13], v[32:47]
	s_add_i32 m0, s10, 0x4000
	s_nop 0
	global_load_lds_dwordx4 v[202:203], off
	v_lshl_add_u64 v[202:203], s[86:87], 1, v[182:183]
	s_add_i32 m0, s10, 0x6000
	v_add_f32_e32 v201, v201, v198
	v_add_f32_e32 v201, v201, v199
	v_cvt_pk_bf16_f32 v188, v192, v193
	v_cvt_pk_bf16_f32 v189, v194, v195
	v_cvt_pk_bf16_f32 v190, v196, v197
	v_cvt_pk_bf16_f32 v191, v198, v199
	v_mfma_f32_32x32x16_bf16 v[16:31], v[184:187], v[238:241], v[16:31]
	global_load_lds_dwordx4 v[202:203], off
	v_lshl_add_u64 v[202:203], v[202:203], 0, s[92:93]
	s_add_i32 m0, s10, 0x8000
	v_add_f32_e32 v200, v200, v201
	v_add_f32_e32 v218, v218, v200
	s_waitcnt lgkmcnt(0)
	v_mfma_f32_32x32x16_bf16 v[64:79], v[188:191], v[144:147], v[64:79]
	global_load_lds_dwordx4 v[202:203], off
	v_mfma_f32_32x32x16_bf16 v[48:63], v[188:191], v[148:151], v[48:63]
	v_mfma_f32_32x32x16_bf16 v[32:47], v[188:191], v[152:155], v[32:47]
	v_mfma_f32_32x32x16_bf16 v[16:31], v[188:191], v[156:159], v[16:31]
	s_waitcnt vmcnt(5) lgkmcnt(0)
	s_branch .LBB0_530

.Lat1_nodma:
	s_setprio 3
	v_add_u32_e32 v14, s100, v0
	v_add_u32_e32 v15, s100, v212
	v_add_u32_e32 v176, s100, v213
	v_add_u32_e32 v177, s100, v219
	ds_read_b128 v[144:147], v14 offset:0
	ds_read_b128 v[148:151], v15 offset:0
	ds_read_b128 v[152:155], v176 offset:0
	ds_read_b128 v[156:159], v177 offset:0
	ds_read_b128 v[160:163], v14 offset:8192
	ds_read_b128 v[164:167], v15 offset:8192
	ds_read_b128 v[168:171], v176 offset:8192
	ds_read_b128 v[172:175], v177 offset:8192
	ds_read_b128 v[2:5], v14 offset:16384
	ds_read_b128 v[6:9], v15 offset:16384
	ds_read_b128 v[10:13], v176 offset:16384
	ds_read_b128 v[238:241], v177 offset:16384
	s_waitcnt lgkmcnt(8)
	v_mfma_f32_32x32x16_bf16 v[80:95], v[144:147], v[132:135], 0
	v_mfma_f32_32x32x16_bf16 v[80:95], v[148:151], v[128:131], v[80:95]
	v_mfma_f32_32x32x16_bf16 v[80:95], v[152:155], v[124:127], v[80:95]
	v_mfma_f32_32x32x16_bf16 v[80:95], v[156:159], v[120:123], v[80:95]
	ds_read_b128 v[144:147], v14 offset:4096
	ds_read_b128 v[148:151], v15 offset:4096
	ds_read_b128 v[152:155], v176 offset:4096
	ds_read_b128 v[156:159], v177 offset:4096
	s_waitcnt lgkmcnt(8)
	v_mfma_f32_32x32x16_bf16 v[80:95], v[160:163], v[116:119], v[80:95]
	v_mfma_f32_32x32x16_bf16 v[80:95], v[164:167], v[112:115], v[80:95]
	v_mfma_f32_32x32x16_bf16 v[80:95], v[168:171], v[108:111], v[80:95]
	v_mfma_f32_32x32x16_bf16 v[80:95], v[172:175], v[104:107], v[80:95]
	ds_read_b128 v[160:163], v14 offset:12288
	ds_read_b128 v[164:167], v15 offset:12288
	ds_read_b128 v[168:171], v176 offset:12288
	ds_read_b128 v[172:175], v177 offset:12288
	s_waitcnt lgkmcnt(8)
	v_mfma_f32_32x32x16_bf16 v[80:95], v[2:5], v[100:103], v[80:95]
	v_mfma_f32_32x32x16_bf16 v[80:95], v[6:9], v[140:143], v[80:95]
	v_mfma_f32_32x32x16_bf16 v[80:95], v[10:13], v[96:99], v[80:95]
	v_mfma_f32_32x32x16_bf16 v[80:95], v[238:241], v[136:139], v[80:95]
	s_setprio 2
	s_setprio 3
	ds_read_b128 v[2:5], v14 offset:20480
	ds_read_b128 v[6:9], v15 offset:20480
	ds_read_b128 v[10:13], v176 offset:20480
	ds_read_b128 v[238:241], v177 offset:20480
	s_setprio 2
	s_waitcnt lgkmcnt(8)
	v_mfma_f32_32x32x16_bf16 v[184:199], v[144:147], v[132:135], 0
	v_mfma_f32_32x32x16_bf16 v[184:199], v[148:151], v[128:131], v[184:199]
	v_mfma_f32_32x32x16_bf16 v[184:199], v[152:155], v[124:127], v[184:199]
	v_mfma_f32_32x32x16_bf16 v[184:199], v[156:159], v[120:123], v[184:199]
	s_setprio 3
	ds_read_b128 v[144:147], v14 offset:24576
	ds_read_b128 v[148:151], v14 offset:28672
	ds_read_b128 v[152:155], v14 offset:32768
	ds_read_b128 v[156:159], v14 offset:36864
	s_setprio 2
	s_waitcnt lgkmcnt(8)
	v_mfma_f32_32x32x16_bf16 v[184:199], v[160:163], v[116:119], v[184:199]
	v_med3_f32 v80, v80, s4, v236
	v_exp_f32_e32 v80, v80
	v_med3_f32 v81, v81, s4, v236
	v_exp_f32_e32 v81, v81
	v_mfma_f32_32x32x16_bf16 v[184:199], v[164:167], v[112:115], v[184:199]
	v_med3_f32 v82, v82, s4, v236
	v_exp_f32_e32 v82, v82
	v_med3_f32 v83, v83, s4, v236
	v_exp_f32_e32 v83, v83
	v_mfma_f32_32x32x16_bf16 v[184:199], v[168:171], v[108:111], v[184:199]
	v_med3_f32 v84, v84, s4, v236
	v_exp_f32_e32 v84, v84
	v_med3_f32 v85, v85, s4, v236
	v_exp_f32_e32 v85, v85
	v_mfma_f32_32x32x16_bf16 v[184:199], v[172:175], v[104:107], v[184:199]
	v_med3_f32 v86, v86, s4, v236
	v_exp_f32_e32 v86, v86
	v_med3_f32 v87, v87, s4, v236
	v_exp_f32_e32 v87, v87
	s_setprio 3
	ds_read_b128 v[160:163], v15 offset:24576
	ds_read_b128 v[164:167], v15 offset:28672
	ds_read_b128 v[168:171], v15 offset:32768
	ds_read_b128 v[172:175], v15 offset:36864
	s_setprio 2
	s_waitcnt lgkmcnt(8)
	v_mfma_f32_32x32x16_bf16 v[184:199], v[2:5], v[100:103], v[184:199]
	v_med3_f32 v88, v88, s4, v236
	v_exp_f32_e32 v88, v88
	v_med3_f32 v89, v89, s4, v236
	v_exp_f32_e32 v89, v89
	v_add_f32_e32 v200, v80, v81
	v_add_f32_e32 v200, v200, v82
	v_mfma_f32_32x32x16_bf16 v[184:199], v[6:9], v[140:143], v[184:199]
	v_med3_f32 v90, v90, s4, v236
	v_exp_f32_e32 v90, v90
	v_med3_f32 v91, v91, s4, v236
	v_exp_f32_e32 v91, v91
	v_add_f32_e32 v200, v200, v83
	v_add_f32_e32 v200, v200, v84
	v_mfma_f32_32x32x16_bf16 v[184:199], v[10:13], v[96:99], v[184:199]
	v_med3_f32 v92, v92, s4, v236
	v_exp_f32_e32 v92, v92
	v_med3_f32 v93, v93, s4, v236
	v_exp_f32_e32 v93, v93
	v_add_f32_e32 v200, v200, v85
	v_add_f32_e32 v200, v200, v86
	v_mfma_f32_32x32x16_bf16 v[184:199], v[238:241], v[136:139], v[184:199]
	v_med3_f32 v94, v94, s4, v236
	v_exp_f32_e32 v94, v94
	v_med3_f32 v95, v95, s4, v236
	v_exp_f32_e32 v95, v95
	v_add_f32_e32 v200, v200, v87
	s_setprio 1
	s_setprio 3
	ds_read_b128 v[2:5], v176 offset:24576
	ds_read_b128 v[6:9], v176 offset:28672
	ds_read_b128 v[10:13], v176 offset:32768
	ds_read_b128 v[238:241], v176 offset:36864
	s_setprio 1
	v_cvt_pk_bf16_f32 v80, v80, v81
	v_cvt_pk_bf16_f32 v81, v82, v83
	v_cvt_pk_bf16_f32 v82, v84, v85
	v_cvt_pk_bf16_f32 v83, v86, v87
	v_add_f32_e32 v200, v200, v88
	v_add_f32_e32 v200, v200, v89
	s_waitcnt lgkmcnt(8)
	v_mfma_f32_32x32x16_bf16 v[64:79], v[80:83], v[144:147], v[64:79]
	v_med3_f32 v184, v184, s4, v236
	v_exp_f32_e32 v184, v184
	v_med3_f32 v185, v185, s4, v236
	v_exp_f32_e32 v185, v185
	v_add_f32_e32 v200, v200, v90
	v_add_f32_e32 v200, v200, v91
	v_mfma_f32_32x32x16_bf16 v[48:63], v[80:83], v[148:151], v[48:63]
	v_med3_f32 v186, v186, s4, v236
	v_exp_f32_e32 v186, v186
	v_med3_f32 v187, v187, s4, v236
	v_exp_f32_e32 v187, v187
	v_add_f32_e32 v200, v200, v92
	v_add_f32_e32 v200, v200, v93
	v_mfma_f32_32x32x16_bf16 v[32:47], v[80:83], v[152:155], v[32:47]
	v_med3_f32 v188, v188, s4, v236
	v_exp_f32_e32 v188, v188
	v_med3_f32 v189, v189, s4, v236
	v_exp_f32_e32 v189, v189
	v_add_f32_e32 v200, v200, v94
	v_add_f32_e32 v200, v200, v95
	v_mfma_f32_32x32x16_bf16 v[16:31], v[80:83], v[156:159], v[16:31]
	v_med3_f32 v190, v190, s4, v236
	v_exp_f32_e32 v190, v190
	v_med3_f32 v191, v191, s4, v236
	v_exp_f32_e32 v191, v191
	v_cvt_pk_bf16_f32 v84, v88, v89
	v_cvt_pk_bf16_f32 v85, v90, v91
	v_cvt_pk_bf16_f32 v86, v92, v93
	v_cvt_pk_bf16_f32 v87, v94, v95
	s_setprio 3
	ds_read_b128 v[144:147], v177 offset:24576
	ds_read_b128 v[148:151], v177 offset:28672
	ds_read_b128 v[152:155], v177 offset:32768
	ds_read_b128 v[156:159], v177 offset:36864
	s_setprio 1
	s_waitcnt lgkmcnt(8)
	v_mfma_f32_32x32x16_bf16 v[64:79], v[84:87], v[160:163], v[64:79]
	v_med3_f32 v192, v192, s4, v236
	v_exp_f32_e32 v192, v192
	v_med3_f32 v193, v193, s4, v236
	v_exp_f32_e32 v193, v193
	v_add_f32_e32 v201, v184, v185
	v_add_f32_e32 v201, v201, v186
	v_mfma_f32_32x32x16_bf16 v[48:63], v[84:87], v[164:167], v[48:63]
	v_med3_f32 v194, v194, s4, v236
	v_exp_f32_e32 v194, v194
	v_med3_f32 v195, v195, s4, v236
	v_exp_f32_e32 v195, v195
	v_add_f32_e32 v201, v201, v187
	v_add_f32_e32 v201, v201, v188
	v_mfma_f32_32x32x16_bf16 v[32:47], v[84:87], v[168:171], v[32:47]
	v_med3_f32 v196, v196, s4, v236
	v_exp_f32_e32 v196, v196
	v_med3_f32 v197, v197, s4, v236
	v_exp_f32_e32 v197, v197
	v_add_f32_e32 v201, v201, v189
	v_mfma_f32_32x32x16_bf16 v[16:31], v[84:87], v[172:175], v[16:31]
	v_med3_f32 v198, v198, s4, v236
	v_exp_f32_e32 v198, v198
	v_med3_f32 v199, v199, s4, v236
	v_exp_f32_e32 v199, v199
	v_add_f32_e32 v201, v201, v190
	v_cvt_pk_bf16_f32 v184, v184, v185
	v_cvt_pk_bf16_f32 v185, v186, v187
	v_cvt_pk_bf16_f32 v186, v188, v189
	v_cvt_pk_bf16_f32 v187, v190, v191
	v_add_f32_e32 v201, v201, v191
	s_setprio 0
	s_waitcnt lgkmcnt(4)
	v_mfma_f32_32x32x16_bf16 v[64:79], v[184:187], v[2:5], v[64:79]
	v_add_f32_e32 v201, v201, v192
	v_add_f32_e32 v201, v201, v193
	v_add_f32_e32 v201, v201, v194
	v_mfma_f32_32x32x16_bf16 v[48:63], v[184:187], v[6:9], v[48:63]
	v_add_f32_e32 v201, v201, v195
	v_add_f32_e32 v201, v201, v196
	v_add_f32_e32 v201, v201, v197
	v_mfma_f32_32x32x16_bf16 v[32:47], v[184:187], v[10:13], v[32:47]
	v_add_f32_e32 v201, v201, v198
	v_add_f32_e32 v201, v201, v199
	v_cvt_pk_bf16_f32 v188, v192, v193
	v_cvt_pk_bf16_f32 v189, v194, v195
	v_cvt_pk_bf16_f32 v190, v196, v197
	v_cvt_pk_bf16_f32 v191, v198, v199
	v_mfma_f32_32x32x16_bf16 v[16:31], v[184:187], v[238:241], v[16:31]
	v_add_f32_e32 v200, v200, v201
	v_add_f32_e32 v218, v218, v200
	s_waitcnt lgkmcnt(0)
	v_mfma_f32_32x32x16_bf16 v[64:79], v[188:191], v[144:147], v[64:79]
	v_mfma_f32_32x32x16_bf16 v[48:63], v[188:191], v[148:151], v[48:63]
	v_mfma_f32_32x32x16_bf16 v[32:47], v[188:191], v[152:155], v[32:47]
	v_mfma_f32_32x32x16_bf16 v[16:31], v[188:191], v[156:159], v[16:31]
	s_waitcnt vmcnt(0) lgkmcnt(0)
	s_branch .LBB0_530

.Lat2_dispatch:
	s_cbranch_scc1 .LBB0_583
	s_cbranch_vccnz .Lat2_skip
	s_and_b64 vcc, exec, s[22:23]
	s_cbranch_vccnz .Lat2_nodma
	s_setprio 3
	v_add_u32_e32 v198, s100, v218
	v_add_u32_e32 v199, s100, v219
	v_add_u32_e32 v200, s100, v209
	v_add_u32_e32 v201, s100, v208
	ds_read_b128 v[130:133], v198 offset:0
	ds_read_b128 v[134:137], v199 offset:0
	ds_read_b128 v[138:141], v200 offset:0
	ds_read_b128 v[142:145], v201 offset:0
	ds_read_b128 v[146:149], v198 offset:8192
	ds_read_b128 v[150:153], v199 offset:8192
	ds_read_b128 v[154:157], v200 offset:8192
	ds_read_b128 v[158:161], v201 offset:8192
	ds_read_b128 v[162:165], v198 offset:16384
	ds_read_b128 v[166:169], v199 offset:16384
	ds_read_b128 v[170:173], v200 offset:16384
	ds_read_b128 v[176:179], v201 offset:16384
	s_waitcnt lgkmcnt(8)
	v_mfma_f32_32x32x16_bf16 v[66:81], v[130:133], v[118:121], 0
	v_mfma_f32_32x32x16_bf16 v[66:81], v[134:137], v[114:117], v[66:81]
	v_mfma_f32_32x32x16_bf16 v[66:81], v[138:141], v[110:113], v[66:81]
	v_mfma_f32_32x32x16_bf16 v[66:81], v[142:145], v[106:109], v[66:81]
	ds_read_b128 v[130:133], v198 offset:4096
	ds_read_b128 v[134:137], v199 offset:4096
	ds_read_b128 v[138:141], v200 offset:4096
	ds_read_b128 v[142:145], v201 offset:4096
	s_waitcnt lgkmcnt(8)
	v_mfma_f32_32x32x16_bf16 v[66:81], v[146:149], v[102:105], v[66:81]
	v_mfma_f32_32x32x16_bf16 v[66:81], v[150:153], v[98:101], v[66:81]
	v_mfma_f32_32x32x16_bf16 v[66:81], v[154:157], v[94:97], v[66:81]
	v_mfma_f32_32x32x16_bf16 v[66:81], v[158:161], v[90:93], v[66:81]
	ds_read_b128 v[146:149], v198 offset:12288
	ds_read_b128 v[150:153], v199 offset:12288
	ds_read_b128 v[154:157], v200 offset:12288
	ds_read_b128 v[158:161], v201 offset:12288
	s_waitcnt lgkmcnt(8)
	v_mfma_f32_32x32x16_bf16 v[66:81], v[162:165], v[86:89], v[66:81]
	v_mfma_f32_32x32x16_bf16 v[66:81], v[166:169], v[126:129], v[66:81]
	v_mfma_f32_32x32x16_bf16 v[66:81], v[170:173], v[82:85], v[66:81]
	v_mfma_f32_32x32x16_bf16 v[66:81], v[176:179], v[122:125], v[66:81]
	s_setprio 2
	s_setprio 3
	ds_read_b128 v[162:165], v198 offset:20480
	ds_read_b128 v[166:169], v199 offset:20480
	ds_read_b128 v[170:173], v200 offset:20480
	ds_read_b128 v[176:179], v201 offset:20480
	s_setprio 2
	s_waitcnt lgkmcnt(8)
	v_mfma_f32_32x32x16_bf16 v[182:197], v[130:133], v[118:121], 0
	v_mfma_f32_32x32x16_bf16 v[182:197], v[134:137], v[114:117], v[182:197]
	v_mfma_f32_32x32x16_bf16 v[182:197], v[138:141], v[110:113], v[182:197]
	v_mfma_f32_32x32x16_bf16 v[182:197], v[142:145], v[106:109], v[182:197]
	s_setprio 3
	ds_read_b128 v[130:133], v198 offset:24576
	ds_read_b128 v[134:137], v198 offset:28672
	ds_read_b128 v[138:141], v198 offset:32768
	ds_read_b128 v[142:145], v198 offset:36864
	s_setprio 2
	s_waitcnt lgkmcnt(8)
	v_mfma_f32_32x32x16_bf16 v[182:197], v[146:149], v[102:105], v[182:197]
	v_med3_f32 v66, v66, s4, v236
	v_exp_f32_e32 v66, v66
	v_med3_f32 v67, v67, s4, v236
	v_exp_f32_e32 v67, v67
	v_mfma_f32_32x32x16_bf16 v[182:197], v[150:153], v[98:101], v[182:197]
	v_med3_f32 v68, v68, s4, v236
	v_exp_f32_e32 v68, v68
	v_med3_f32 v69, v69, s4, v236
	v_exp_f32_e32 v69, v69
	v_mfma_f32_32x32x16_bf16 v[182:197], v[154:157], v[94:97], v[182:197]
	v_med3_f32 v70, v70, s4, v236
	v_exp_f32_e32 v70, v70
	v_med3_f32 v71, v71, s4, v236
	v_exp_f32_e32 v71, v71
	v_mfma_f32_32x32x16_bf16 v[182:197], v[158:161], v[90:93], v[182:197]
	v_med3_f32 v72, v72, s4, v236
	v_exp_f32_e32 v72, v72
	v_med3_f32 v73, v73, s4, v236
	v_exp_f32_e32 v73, v73
	s_setprio 3
	ds_read_b128 v[146:149], v199 offset:24576
	ds_read_b128 v[150:153], v199 offset:28672
	ds_read_b128 v[154:157], v199 offset:32768
	ds_read_b128 v[158:161], v199 offset:36864
	s_setprio 2
	s_waitcnt lgkmcnt(8)
	v_mfma_f32_32x32x16_bf16 v[182:197], v[162:165], v[86:89], v[182:197]
	v_med3_f32 v74, v74, s4, v236
	v_exp_f32_e32 v74, v74
	v_med3_f32 v75, v75, s4, v236
	v_exp_f32_e32 v75, v75
	v_add_f32_e32 v202, v66, v67
	v_add_f32_e32 v202, v202, v68
	v_mfma_f32_32x32x16_bf16 v[182:197], v[166:169], v[126:129], v[182:197]
	v_med3_f32 v76, v76, s4, v236
	v_exp_f32_e32 v76, v76
	v_med3_f32 v77, v77, s4, v236
	v_exp_f32_e32 v77, v77
	v_add_f32_e32 v202, v202, v69
	v_add_f32_e32 v202, v202, v70
	v_mfma_f32_32x32x16_bf16 v[182:197], v[170:173], v[82:85], v[182:197]
	v_med3_f32 v78, v78, s4, v236
	v_exp_f32_e32 v78, v78
	v_med3_f32 v79, v79, s4, v236
	v_exp_f32_e32 v79, v79
	v_add_f32_e32 v202, v202, v71
	v_add_f32_e32 v202, v202, v72
	v_mfma_f32_32x32x16_bf16 v[182:197], v[176:179], v[122:125], v[182:197]
	v_med3_f32 v80, v80, s4, v236
	v_exp_f32_e32 v80, v80
	v_med3_f32 v81, v81, s4, v236
	v_exp_f32_e32 v81, v81
	v_add_f32_e32 v202, v202, v73
	s_setprio 1
	s_setprio 3
	ds_read_b128 v[162:165], v200 offset:24576
	ds_read_b128 v[166:169], v200 offset:28672
	ds_read_b128 v[170:173], v200 offset:32768
	ds_read_b128 v[176:179], v200 offset:36864
	s_setprio 1
	v_cvt_pk_bf16_f32 v66, v66, v67
	v_cvt_pk_bf16_f32 v67, v68, v69
	v_cvt_pk_bf16_f32 v68, v70, v71
	v_cvt_pk_bf16_f32 v69, v72, v73
	v_add_f32_e32 v202, v202, v74
	v_add_f32_e32 v202, v202, v75
	s_waitcnt lgkmcnt(8)
	v_mfma_f32_32x32x16_bf16 v[50:65], v[66:69], v[130:133], v[50:65]
	v_med3_f32 v182, v182, s4, v236
	v_exp_f32_e32 v182, v182
	v_med3_f32 v183, v183, s4, v236
	v_exp_f32_e32 v183, v183
	v_add_f32_e32 v202, v202, v76
	v_add_f32_e32 v202, v202, v77
	v_mfma_f32_32x32x16_bf16 v[34:49], v[66:69], v[134:137], v[34:49]
	v_med3_f32 v184, v184, s4, v236
	v_exp_f32_e32 v184, v184
	v_med3_f32 v185, v185, s4, v236
	v_exp_f32_e32 v185, v185
	v_add_f32_e32 v202, v202, v78
	v_add_f32_e32 v202, v202, v79
	v_mfma_f32_32x32x16_bf16 v[18:33], v[66:69], v[138:141], v[18:33]
	v_med3_f32 v186, v186, s4, v236
	v_exp_f32_e32 v186, v186
	v_med3_f32 v187, v187, s4, v236
	v_exp_f32_e32 v187, v187
	v_add_f32_e32 v202, v202, v80
	v_add_f32_e32 v202, v202, v81
	v_mfma_f32_32x32x16_bf16 v[2:17], v[66:69], v[142:145], v[2:17]
	v_med3_f32 v188, v188, s4, v236
	v_exp_f32_e32 v188, v188
	v_med3_f32 v189, v189, s4, v236
	v_exp_f32_e32 v189, v189
	v_cvt_pk_bf16_f32 v70, v74, v75
	v_cvt_pk_bf16_f32 v71, v76, v77
	v_cvt_pk_bf16_f32 v72, v78, v79
	v_cvt_pk_bf16_f32 v73, v80, v81
	s_setprio 3
	ds_read_b128 v[130:133], v201 offset:24576
	ds_read_b128 v[134:137], v201 offset:28672
	ds_read_b128 v[138:141], v201 offset:32768
	ds_read_b128 v[142:145], v201 offset:36864
	s_setprio 1
	s_waitcnt lgkmcnt(8)
	v_mfma_f32_32x32x16_bf16 v[50:65], v[70:73], v[146:149], v[50:65]
	v_med3_f32 v190, v190, s4, v236
	v_exp_f32_e32 v190, v190
	v_med3_f32 v191, v191, s4, v236
	v_exp_f32_e32 v191, v191
	v_add_f32_e32 v203, v182, v183
	v_add_f32_e32 v203, v203, v184
	v_mfma_f32_32x32x16_bf16 v[34:49], v[70:73], v[150:153], v[34:49]
	v_med3_f32 v192, v192, s4, v236
	v_exp_f32_e32 v192, v192
	v_med3_f32 v193, v193, s4, v236
	v_exp_f32_e32 v193, v193
	v_add_f32_e32 v203, v203, v185
	v_add_f32_e32 v203, v203, v186
	v_mfma_f32_32x32x16_bf16 v[18:33], v[70:73], v[154:157], v[18:33]
	v_med3_f32 v194, v194, s4, v236
	v_exp_f32_e32 v194, v194
	v_med3_f32 v195, v195, s4, v236
	v_exp_f32_e32 v195, v195
	v_add_f32_e32 v203, v203, v187
	v_mfma_f32_32x32x16_bf16 v[2:17], v[70:73], v[158:161], v[2:17]
	v_med3_f32 v196, v196, s4, v236
	v_exp_f32_e32 v196, v196
	v_med3_f32 v197, v197, s4, v236
	v_exp_f32_e32 v197, v197
	v_add_f32_e32 v203, v203, v188
	v_cvt_pk_bf16_f32 v182, v182, v183
	v_cvt_pk_bf16_f32 v183, v184, v185
	v_cvt_pk_bf16_f32 v184, v186, v187
	v_cvt_pk_bf16_f32 v185, v188, v189
	v_add_f32_e32 v203, v203, v189
	s_setprio 0
	s_waitcnt lgkmcnt(4)
	v_mfma_f32_32x32x16_bf16 v[50:65], v[182:185], v[162:165], v[50:65]
	v_mad_u64_u32 v[204:205], s[10:11], s86, v228, v[174:175]
	s_mul_i32 s10, s7, 0xa000
	s_add_i32 s10, s0, s10
	s_mov_b32 m0, s10
	v_lshl_add_u64 v[206:207], v[204:205], 0, s[94:95]
	global_load_lds_dwordx4 v[204:205], off
	v_add_f32_e32 v203, v203, v190
	v_add_f32_e32 v203, v203, v191
	v_add_f32_e32 v203, v203, v192
	v_mfma_f32_32x32x16_bf16 v[34:49], v[182:185], v[166:169], v[34:49]
	s_add_i32 m0, s10, 0x2000
	v_lshl_add_u64 v[204:205], v[204:205], 0, s[96:97]
	global_load_lds_dwordx4 v[206:207], off
	v_add_f32_e32 v203, v203, v193
	v_add_f32_e32 v203, v203, v194
	v_add_f32_e32 v203, v203, v195
	v_mfma_f32_32x32x16_bf16 v[18:33], v[182:185], v[170:173], v[18:33]
	s_add_i32 m0, s10, 0x4000
	s_nop 0
	global_load_lds_dwordx4 v[204:205], off
	v_lshl_add_u64 v[204:205], s[86:87], 1, v[180:181]
	s_add_i32 m0, s10, 0x6000
	v_add_f32_e32 v203, v203, v196
	v_add_f32_e32 v203, v203, v197
	v_cvt_pk_bf16_f32 v186, v190, v191
	v_cvt_pk_bf16_f32 v187, v192, v193
	v_cvt_pk_bf16_f32 v188, v194, v195
	v_cvt_pk_bf16_f32 v189, v196, v197
	v_mfma_f32_32x32x16_bf16 v[2:17], v[182:185], v[176:179], v[2:17]
	global_load_lds_dwordx4 v[204:205], off
	v_lshl_add_u64 v[204:205], v[204:205], 0, s[92:93]
	s_add_i32 m0, s10, 0x8000
	v_add_f32_e32 v202, v202, v203
	v_add_f32_e32 v0, v0, v202
	s_waitcnt lgkmcnt(0)
	v_mfma_f32_32x32x16_bf16 v[50:65], v[186:189], v[130:133], v[50:65]
	global_load_lds_dwordx4 v[204:205], off
	v_mfma_f32_32x32x16_bf16 v[34:49], v[186:189], v[134:137], v[34:49]
	v_mfma_f32_32x32x16_bf16 v[18:33], v[186:189], v[138:141], v[18:33]
	v_mfma_f32_32x32x16_bf16 v[2:17], v[186:189], v[142:145], v[2:17]
	s_waitcnt vmcnt(5) lgkmcnt(0)
	s_branch .LBB0_573

.Lat2_nodma:
	s_setprio 3
	v_add_u32_e32 v198, s100, v218
	v_add_u32_e32 v199, s100, v219
	v_add_u32_e32 v200, s100, v209
	v_add_u32_e32 v201, s100, v208
	ds_read_b128 v[130:133], v198 offset:0
	ds_read_b128 v[134:137], v199 offset:0
	ds_read_b128 v[138:141], v200 offset:0
	ds_read_b128 v[142:145], v201 offset:0
	ds_read_b128 v[146:149], v198 offset:8192
	ds_read_b128 v[150:153], v199 offset:8192
	ds_read_b128 v[154:157], v200 offset:8192
	ds_read_b128 v[158:161], v201 offset:8192
	ds_read_b128 v[162:165], v198 offset:16384
	ds_read_b128 v[166:169], v199 offset:16384
	ds_read_b128 v[170:173], v200 offset:16384
	ds_read_b128 v[176:179], v201 offset:16384
	s_waitcnt lgkmcnt(8)
	v_mfma_f32_32x32x16_bf16 v[66:81], v[130:133], v[118:121], 0
	v_mfma_f32_32x32x16_bf16 v[66:81], v[134:137], v[114:117], v[66:81]
	v_mfma_f32_32x32x16_bf16 v[66:81], v[138:141], v[110:113], v[66:81]
	v_mfma_f32_32x32x16_bf16 v[66:81], v[142:145], v[106:109], v[66:81]
	ds_read_b128 v[130:133], v198 offset:4096
	ds_read_b128 v[134:137], v199 offset:4096
	ds_read_b128 v[138:141], v200 offset:4096
	ds_read_b128 v[142:145], v201 offset:4096
	s_waitcnt lgkmcnt(8)
	v_mfma_f32_32x32x16_bf16 v[66:81], v[146:149], v[102:105], v[66:81]
	v_mfma_f32_32x32x16_bf16 v[66:81], v[150:153], v[98:101], v[66:81]
	v_mfma_f32_32x32x16_bf16 v[66:81], v[154:157], v[94:97], v[66:81]
	v_mfma_f32_32x32x16_bf16 v[66:81], v[158:161], v[90:93], v[66:81]
	ds_read_b128 v[146:149], v198 offset:12288
	ds_read_b128 v[150:153], v199 offset:12288
	ds_read_b128 v[154:157], v200 offset:12288
	ds_read_b128 v[158:161], v201 offset:12288
	s_waitcnt lgkmcnt(8)
	v_mfma_f32_32x32x16_bf16 v[66:81], v[162:165], v[86:89], v[66:81]
	v_mfma_f32_32x32x16_bf16 v[66:81], v[166:169], v[126:129], v[66:81]
	v_mfma_f32_32x32x16_bf16 v[66:81], v[170:173], v[82:85], v[66:81]
	v_mfma_f32_32x32x16_bf16 v[66:81], v[176:179], v[122:125], v[66:81]
	s_setprio 2
	s_setprio 3
	ds_read_b128 v[162:165], v198 offset:20480
	ds_read_b128 v[166:169], v199 offset:20480
	ds_read_b128 v[170:173], v200 offset:20480
	ds_read_b128 v[176:179], v201 offset:20480
	s_setprio 2
	s_waitcnt lgkmcnt(8)
	v_mfma_f32_32x32x16_bf16 v[182:197], v[130:133], v[118:121], 0
	v_mfma_f32_32x32x16_bf16 v[182:197], v[134:137], v[114:117], v[182:197]
	v_mfma_f32_32x32x16_bf16 v[182:197], v[138:141], v[110:113], v[182:197]
	v_mfma_f32_32x32x16_bf16 v[182:197], v[142:145], v[106:109], v[182:197]
	s_setprio 3
	ds_read_b128 v[130:133], v198 offset:24576
	ds_read_b128 v[134:137], v198 offset:28672
	ds_read_b128 v[138:141], v198 offset:32768
	ds_read_b128 v[142:145], v198 offset:36864
	s_setprio 2
	s_waitcnt lgkmcnt(8)
	v_mfma_f32_32x32x16_bf16 v[182:197], v[146:149], v[102:105], v[182:197]
	v_med3_f32 v66, v66, s4, v236
	v_exp_f32_e32 v66, v66
	v_med3_f32 v67, v67, s4, v236
	v_exp_f32_e32 v67, v67
	v_mfma_f32_32x32x16_bf16 v[182:197], v[150:153], v[98:101], v[182:197]
	v_med3_f32 v68, v68, s4, v236
	v_exp_f32_e32 v68, v68
	v_med3_f32 v69, v69, s4, v236
	v_exp_f32_e32 v69, v69
	v_mfma_f32_32x32x16_bf16 v[182:197], v[154:157], v[94:97], v[182:197]
	v_med3_f32 v70, v70, s4, v236
	v_exp_f32_e32 v70, v70
	v_med3_f32 v71, v71, s4, v236
	v_exp_f32_e32 v71, v71
	v_mfma_f32_32x32x16_bf16 v[182:197], v[158:161], v[90:93], v[182:197]
	v_med3_f32 v72, v72, s4, v236
	v_exp_f32_e32 v72, v72
	v_med3_f32 v73, v73, s4, v236
	v_exp_f32_e32 v73, v73
	s_setprio 3
	ds_read_b128 v[146:149], v199 offset:24576
	ds_read_b128 v[150:153], v199 offset:28672
	ds_read_b128 v[154:157], v199 offset:32768
	ds_read_b128 v[158:161], v199 offset:36864
	s_setprio 2
	s_waitcnt lgkmcnt(8)
	v_mfma_f32_32x32x16_bf16 v[182:197], v[162:165], v[86:89], v[182:197]
	v_med3_f32 v74, v74, s4, v236
	v_exp_f32_e32 v74, v74
	v_med3_f32 v75, v75, s4, v236
	v_exp_f32_e32 v75, v75
	v_add_f32_e32 v202, v66, v67
	v_add_f32_e32 v202, v202, v68
	v_mfma_f32_32x32x16_bf16 v[182:197], v[166:169], v[126:129], v[182:197]
	v_med3_f32 v76, v76, s4, v236
	v_exp_f32_e32 v76, v76
	v_med3_f32 v77, v77, s4, v236
	v_exp_f32_e32 v77, v77
	v_add_f32_e32 v202, v202, v69
	v_add_f32_e32 v202, v202, v70
	v_mfma_f32_32x32x16_bf16 v[182:197], v[170:173], v[82:85], v[182:197]
	v_med3_f32 v78, v78, s4, v236
	v_exp_f32_e32 v78, v78
	v_med3_f32 v79, v79, s4, v236
	v_exp_f32_e32 v79, v79
	v_add_f32_e32 v202, v202, v71
	v_add_f32_e32 v202, v202, v72
	v_mfma_f32_32x32x16_bf16 v[182:197], v[176:179], v[122:125], v[182:197]
	v_med3_f32 v80, v80, s4, v236
	v_exp_f32_e32 v80, v80
	v_med3_f32 v81, v81, s4, v236
	v_exp_f32_e32 v81, v81
	v_add_f32_e32 v202, v202, v73
	s_setprio 1
	s_setprio 3
	ds_read_b128 v[162:165], v200 offset:24576
	ds_read_b128 v[166:169], v200 offset:28672
	ds_read_b128 v[170:173], v200 offset:32768
	ds_read_b128 v[176:179], v200 offset:36864
	s_setprio 1
	v_cvt_pk_bf16_f32 v66, v66, v67
	v_cvt_pk_bf16_f32 v67, v68, v69
	v_cvt_pk_bf16_f32 v68, v70, v71
	v_cvt_pk_bf16_f32 v69, v72, v73
	v_add_f32_e32 v202, v202, v74
	v_add_f32_e32 v202, v202, v75
	s_waitcnt lgkmcnt(8)
	v_mfma_f32_32x32x16_bf16 v[50:65], v[66:69], v[130:133], v[50:65]
	v_med3_f32 v182, v182, s4, v236
	v_exp_f32_e32 v182, v182
	v_med3_f32 v183, v183, s4, v236
	v_exp_f32_e32 v183, v183
	v_add_f32_e32 v202, v202, v76
	v_add_f32_e32 v202, v202, v77
	v_mfma_f32_32x32x16_bf16 v[34:49], v[66:69], v[134:137], v[34:49]
	v_med3_f32 v184, v184, s4, v236
	v_exp_f32_e32 v184, v184
	v_med3_f32 v185, v185, s4, v236
	v_exp_f32_e32 v185, v185
	v_add_f32_e32 v202, v202, v78
	v_add_f32_e32 v202, v202, v79
	v_mfma_f32_32x32x16_bf16 v[18:33], v[66:69], v[138:141], v[18:33]
	v_med3_f32 v186, v186, s4, v236
	v_exp_f32_e32 v186, v186
	v_med3_f32 v187, v187, s4, v236
	v_exp_f32_e32 v187, v187
	v_add_f32_e32 v202, v202, v80
	v_add_f32_e32 v202, v202, v81
	v_mfma_f32_32x32x16_bf16 v[2:17], v[66:69], v[142:145], v[2:17]
	v_med3_f32 v188, v188, s4, v236
	v_exp_f32_e32 v188, v188
	v_med3_f32 v189, v189, s4, v236
	v_exp_f32_e32 v189, v189
	v_cvt_pk_bf16_f32 v70, v74, v75
	v_cvt_pk_bf16_f32 v71, v76, v77
	v_cvt_pk_bf16_f32 v72, v78, v79
	v_cvt_pk_bf16_f32 v73, v80, v81
	s_setprio 3
	ds_read_b128 v[130:133], v201 offset:24576
	ds_read_b128 v[134:137], v201 offset:28672
	ds_read_b128 v[138:141], v201 offset:32768
	ds_read_b128 v[142:145], v201 offset:36864
	s_setprio 1
	s_waitcnt lgkmcnt(8)
	v_mfma_f32_32x32x16_bf16 v[50:65], v[70:73], v[146:149], v[50:65]
	v_med3_f32 v190, v190, s4, v236
	v_exp_f32_e32 v190, v190
	v_med3_f32 v191, v191, s4, v236
	v_exp_f32_e32 v191, v191
	v_add_f32_e32 v203, v182, v183
	v_add_f32_e32 v203, v203, v184
	v_mfma_f32_32x32x16_bf16 v[34:49], v[70:73], v[150:153], v[34:49]
	v_med3_f32 v192, v192, s4, v236
	v_exp_f32_e32 v192, v192
	v_med3_f32 v193, v193, s4, v236
	v_exp_f32_e32 v193, v193
	v_add_f32_e32 v203, v203, v185
	v_add_f32_e32 v203, v203, v186
	v_mfma_f32_32x32x16_bf16 v[18:33], v[70:73], v[154:157], v[18:33]
	v_med3_f32 v194, v194, s4, v236
	v_exp_f32_e32 v194, v194
	v_med3_f32 v195, v195, s4, v236
	v_exp_f32_e32 v195, v195
	v_add_f32_e32 v203, v203, v187
	v_mfma_f32_32x32x16_bf16 v[2:17], v[70:73], v[158:161], v[2:17]
	v_med3_f32 v196, v196, s4, v236
	v_exp_f32_e32 v196, v196
	v_med3_f32 v197, v197, s4, v236
	v_exp_f32_e32 v197, v197
	v_add_f32_e32 v203, v203, v188
	v_cvt_pk_bf16_f32 v182, v182, v183
	v_cvt_pk_bf16_f32 v183, v184, v185
	v_cvt_pk_bf16_f32 v184, v186, v187
	v_cvt_pk_bf16_f32 v185, v188, v189
	v_add_f32_e32 v203, v203, v189
	s_setprio 0
	s_waitcnt lgkmcnt(4)
	v_mfma_f32_32x32x16_bf16 v[50:65], v[182:185], v[162:165], v[50:65]
	v_add_f32_e32 v203, v203, v190
	v_add_f32_e32 v203, v203, v191
	v_add_f32_e32 v203, v203, v192
	v_mfma_f32_32x32x16_bf16 v[34:49], v[182:185], v[166:169], v[34:49]
	v_add_f32_e32 v203, v203, v193
	v_add_f32_e32 v203, v203, v194
	v_add_f32_e32 v203, v203, v195
	v_mfma_f32_32x32x16_bf16 v[18:33], v[182:185], v[170:173], v[18:33]
	v_add_f32_e32 v203, v203, v196
	v_add_f32_e32 v203, v203, v197
	v_cvt_pk_bf16_f32 v186, v190, v191
	v_cvt_pk_bf16_f32 v187, v192, v193
	v_cvt_pk_bf16_f32 v188, v194, v195
	v_cvt_pk_bf16_f32 v189, v196, v197
	v_mfma_f32_32x32x16_bf16 v[2:17], v[182:185], v[176:179], v[2:17]
	v_add_f32_e32 v202, v202, v203
	v_add_f32_e32 v0, v0, v202
	s_waitcnt lgkmcnt(0)
	v_mfma_f32_32x32x16_bf16 v[50:65], v[186:189], v[130:133], v[50:65]
	v_mfma_f32_32x32x16_bf16 v[34:49], v[186:189], v[134:137], v[34:49]
	v_mfma_f32_32x32x16_bf16 v[18:33], v[186:189], v[138:141], v[18:33]
	v_mfma_f32_32x32x16_bf16 v[2:17], v[186:189], v[142:145], v[2:17]
	s_waitcnt vmcnt(0) lgkmcnt(0)
	s_branch .LBB0_573
